# stack18 + fused LN epilogues: next-modulation shift/scale vectors of the four column blocks loaded together (one wait instead of four)
# speedup vs baseline: 1.0056x; 1.0056x over previous
.LBB0_374:
	s_or_b64 exec, exec, s[8:9]
	s_add_u32 s2, s18, 0x151000
	v_readlane_b32 s6, v253, 5
	s_addc_u32 s8, s19, 0
	v_readlane_b32 s7, v253, 6
	s_and_b64 s[6:7], s[6:7], exec
	v_readlane_b32 s6, v253, 13
	v_readlane_b32 s7, v253, 14
	s_cselect_b32 s2, s2, 0
	s_cselect_b32 s8, s8, 0
	s_and_b64 s[6:7], s[6:7], exec
	s_cselect_b32 s7, s63, s8
	s_cselect_b32 s6, s62, s2
	s_cmp_lg_u64 s[6:7], 0
	s_cselect_b64 s[8:9], -1, 0
	s_add_u32 s2, s6, s28
	s_addc_u32 s11, s7, s29
	s_lshl_b32 s10, s33, 2
	s_waitcnt lgkmcnt(0)
	s_barrier
	s_add_u32 s10, s2, s10
	s_addc_u32 s11, s11, 0
	s_cmp_eq_u64 s[6:7], 0
	v_lshl_add_u64 v[206:207], v[180:181], 2, s[10:11]
	v_mov_b32_e32 v154, 0
	v_mov_b32_e32 v155, 0
	v_mov_b32_e32 v156, 0
	v_mov_b32_e32 v157, 0
	v_mov_b32_e32 v166, 0
	v_mov_b32_e32 v167, 0
	v_mov_b32_e32 v168, 0
	v_mov_b32_e32 v169, 0
	v_mov_b32_e32 v170, 0
	v_mov_b32_e32 v171, 0
	v_mov_b32_e32 v172, 0
	v_mov_b32_e32 v173, 0
	v_mov_b32_e32 v174, 0
	v_mov_b32_e32 v175, 0
	v_mov_b32_e32 v176, 0
	v_mov_b32_e32 v177, 0
	v_mov_b32_e32 v198, 1.0
	v_mov_b32_e32 v199, 1.0
	v_mov_b32_e32 v200, 1.0
	v_mov_b32_e32 v201, 1.0
	v_mov_b32_e32 v202, 1.0
	v_mov_b32_e32 v203, 1.0
	v_mov_b32_e32 v204, 1.0
	v_mov_b32_e32 v205, 1.0
	v_mov_b32_e32 v210, 1.0
	v_mov_b32_e32 v211, 1.0
	v_mov_b32_e32 v212, 1.0
	v_mov_b32_e32 v213, 1.0
	v_mov_b32_e32 v214, 1.0
	v_mov_b32_e32 v215, 1.0
	v_mov_b32_e32 v216, 1.0
	v_mov_b32_e32 v217, 1.0
	v_cndmask_b32_e64 v0, 0, 1, s[8:9]
	v_cmp_ne_u32_e64 s[6:7], 1, v0
	s_waitcnt lgkmcnt(1)
	s_cbranch_scc1 .LBB0_382
	v_add_co_u32_e32 v154, vcc, 0x1000, v206
	s_nop 1
	v_addc_co_u32_e32 v155, vcc, 0, v207, vcc
	global_load_dwordx4 v[214:217], v[154:155], off
	global_load_dwordx4 v[174:177], v[206:207], off
	global_load_dwordx4 v[210:213], v[154:155], off offset:64
	global_load_dwordx4 v[170:173], v[206:207], off offset:64
	global_load_dwordx4 v[202:205], v[154:155], off offset:512
	global_load_dwordx4 v[166:169], v[206:207], off offset:512
	global_load_dwordx4 v[198:201], v[154:155], off offset:576
	global_load_dwordx4 v[154:157], v[206:207], off offset:576
	s_waitcnt vmcnt(0)
	v_pk_add_f32 v[214:215], v[214:215], 1.0 op_sel_hi:[1,0]
	v_pk_add_f32 v[216:217], v[216:217], 1.0 op_sel_hi:[1,0]
	v_pk_add_f32 v[210:211], v[210:211], 1.0 op_sel_hi:[1,0]
	v_pk_add_f32 v[212:213], v[212:213], 1.0 op_sel_hi:[1,0]
	v_pk_add_f32 v[202:203], v[202:203], 1.0 op_sel_hi:[1,0]
	v_pk_add_f32 v[204:205], v[204:205], 1.0 op_sel_hi:[1,0]
	v_pk_add_f32 v[198:199], v[198:199], 1.0 op_sel_hi:[1,0]
	v_pk_add_f32 v[200:201], v[200:201], 1.0 op_sel_hi:[1,0]

.LBB0_1213:
	s_or_b64 exec, exec, s[8:9]
	s_add_u32 s6, s30, s20
	s_addc_u32 s7, s31, s21
	s_waitcnt lgkmcnt(0)
	v_lshl_add_u64 v[162:163], v[196:197], 2, s[6:7]
	v_add_co_u32_e32 v164, vcc, 0x6000, v162
	s_waitcnt lgkmcnt(0)
	s_barrier
	s_nop 0
	v_addc_co_u32_e32 v165, vcc, 0, v163, vcc
	v_add_co_u32_e32 v216, vcc, 0x7000, v162
	s_mov_b64 s[6:7], 0x6000
	s_nop 0
	v_addc_co_u32_e32 v217, vcc, 0, v163, vcc
	v_lshl_add_u64 v[214:215], v[162:163], 0, s[6:7]
	global_load_dwordx4 v[174:177], v[164:165], off
	v_cmp_eq_u32_e32 vcc, 0, v0
	global_load_dwordx2 v[228:229], v[216:217], off
	global_load_dwordx2 v[226:227], v[216:217], off offset:8
	global_load_dwordx4 v[170:173], v[214:215], off offset:64
	global_load_dwordx2 v[224:225], v[216:217], off offset:64
	global_load_dwordx2 v[222:223], v[216:217], off offset:72
	global_load_dwordx4 v[166:169], v[214:215], off offset:512
	global_load_dwordx2 v[220:221], v[216:217], off offset:512
	global_load_dwordx2 v[218:219], v[216:217], off offset:520
	global_load_dwordx4 v[230:233], v[216:217], off offset:576
	global_load_dwordx4 v[162:165], v[214:215], off offset:576
	v_lshl_add_u32 v0, v212, 3, 0
	s_add_u32 s6, s4, s18
	v_lshlrev_b64 v[212:213], 10, v[212:213]
	s_addc_u32 s7, s5, s19
	v_lshl_add_u64 v[212:213], v[212:213], 0, v[196:197]
	v_lshlrev_b64 v[210:211], 10, v[210:211]
	v_lshl_add_u64 v[210:211], v[210:211], 0, v[196:197]
	s_waitcnt vmcnt(0)
	v_pk_add_f32 v[226:227], v[226:227], 1.0 op_sel_hi:[1,0]
	v_pk_add_f32 v[228:229], v[228:229], 1.0 op_sel_hi:[1,0]
	s_nop 0
	s_nop 0
	s_nop 0
	v_pk_add_f32 v[222:223], v[222:223], 1.0 op_sel_hi:[1,0]
	v_pk_add_f32 v[224:225], v[224:225], 1.0 op_sel_hi:[1,0]
	s_nop 0
	s_nop 0
	s_nop 0
	v_pk_add_f32 v[218:219], v[218:219], 1.0 op_sel_hi:[1,0]
	v_pk_add_f32 v[220:221], v[220:221], 1.0 op_sel_hi:[1,0]
	s_nop 0
	s_nop 0
	s_nop 0
	v_pk_add_f32 v[216:217], v[230:231], 1.0 op_sel_hi:[1,0]
	ds_read_b64 v[230:231], v0 offset:8192
	v_pk_add_f32 v[214:215], v[232:233], 1.0 op_sel_hi:[1,0]
	s_waitcnt lgkmcnt(0)
	v_sub_f32_e32 v153, v153, v230
	v_sub_f32_e32 v152, v152, v230
	v_sub_f32_e32 v151, v151, v230
	v_sub_f32_e32 v150, v150, v230
	v_pk_mul_f32 v[150:151], v[230:231], v[150:151] op_sel:[1,0]
	v_pk_mul_f32 v[152:153], v[230:231], v[152:153] op_sel:[1,0]
	v_pk_fma_f32 v[150:151], v[154:155], v[150:151], v[158:159]
	v_pk_fma_f32 v[152:153], v[156:157], v[152:153], v[160:161]
	v_cndmask_b32_e32 v151, v250, v151, vcc
	v_cndmask_b32_e32 v150, v250, v150, vcc
	v_cndmask_b32_e32 v153, v250, v153, vcc
	v_cndmask_b32_e32 v152, v250, v152, vcc
	v_cvt_pk_f16_f32 v231, v152, v153
	v_cvt_pk_f16_f32 v230, v150, v151
	v_pk_fma_f32 v[152:153], v[226:227], v[152:153], v[176:177]
	global_store_dwordx2 v[194:195], v[230:231], off
	v_pk_fma_f32 v[150:151], v[228:229], v[150:151], v[174:175]
	s_nop 0
	v_cvt_pk_bf16_f32 v230, v150, v151
	v_cvt_pk_bf16_f32 v231, v152, v153
	ds_read_b64 v[152:153], v0 offset:8320
	v_lshl_add_u64 v[150:151], v[212:213], 1, s[6:7]
	global_store_dwordx2 v[150:151], v[230:231], off
	s_waitcnt lgkmcnt(0)
	v_sub_f32_e32 v149, v149, v152
	v_sub_f32_e32 v148, v148, v152
	v_sub_f32_e32 v147, v147, v152
	v_sub_f32_e32 v146, v146, v152
	v_pk_mul_f32 v[146:147], v[152:153], v[146:147] op_sel:[1,0]
	v_pk_mul_f32 v[148:149], v[152:153], v[148:149] op_sel:[1,0]
	v_pk_fma_f32 v[146:147], v[154:155], v[146:147], v[158:159]
	v_pk_fma_f32 v[148:149], v[156:157], v[148:149], v[160:161]
	v_cndmask_b32_e32 v147, v250, v147, vcc
	v_cndmask_b32_e32 v146, v250, v146, vcc
	v_cndmask_b32_e32 v149, v250, v149, vcc
	v_cndmask_b32_e32 v148, v250, v148, vcc
	v_cvt_pk_f16_f32 v153, v148, v149
	v_cvt_pk_f16_f32 v152, v146, v147
	v_pk_fma_f32 v[148:149], v[226:227], v[148:149], v[176:177]
	global_store_dwordx2 v[192:193], v[152:153], off
	v_pk_fma_f32 v[146:147], v[228:229], v[146:147], v[174:175]
	s_nop 0
	v_cvt_pk_bf16_f32 v152, v146, v147
	v_cvt_pk_bf16_f32 v153, v148, v149
	ds_read_b64 v[148:149], v0 offset:8448
	v_lshl_add_u64 v[146:147], v[210:211], 1, s[6:7]
	global_store_dwordx2 v[146:147], v[152:153], off
	v_lshlrev_b64 v[152:153], 10, v[208:209]
	v_lshl_add_u64 v[152:153], v[152:153], 0, v[196:197]
	s_waitcnt lgkmcnt(0)
	v_sub_f32_e32 v137, v137, v148
	v_sub_f32_e32 v136, v136, v148
	v_sub_f32_e32 v135, v135, v148
	v_sub_f32_e32 v134, v134, v148
	v_pk_mul_f32 v[134:135], v[148:149], v[134:135] op_sel:[1,0]
	v_pk_mul_f32 v[136:137], v[148:149], v[136:137] op_sel:[1,0]
	v_pk_fma_f32 v[134:135], v[154:155], v[134:135], v[158:159]
	v_pk_fma_f32 v[136:137], v[156:157], v[136:137], v[160:161]
	v_cndmask_b32_e32 v135, v250, v135, vcc
	v_cndmask_b32_e32 v134, v250, v134, vcc
	v_cndmask_b32_e32 v137, v250, v137, vcc
	v_cndmask_b32_e32 v136, v250, v136, vcc
	v_cvt_pk_f16_f32 v149, v136, v137
	v_cvt_pk_f16_f32 v148, v134, v135
	v_pk_fma_f32 v[136:137], v[226:227], v[136:137], v[176:177]
	global_store_dwordx2 v[190:191], v[148:149], off
	v_pk_fma_f32 v[134:135], v[228:229], v[134:135], v[174:175]
	s_nop 0
	v_cvt_pk_bf16_f32 v148, v134, v135
	v_cvt_pk_bf16_f32 v149, v136, v137
	ds_read_b64 v[136:137], v0 offset:8576
	v_lshl_add_u64 v[134:135], v[152:153], 1, s[6:7]
	global_store_dwordx2 v[134:135], v[148:149], off
	v_lshlrev_b64 v[148:149], 10, v[206:207]
	v_lshl_add_u64 v[148:149], v[148:149], 0, v[196:197]
	s_waitcnt lgkmcnt(0)
	v_sub_f32_e32 v121, v121, v136
	v_sub_f32_e32 v120, v120, v136
	v_sub_f32_e32 v119, v119, v136
	v_sub_f32_e32 v118, v118, v136
	v_pk_mul_f32 v[118:119], v[136:137], v[118:119] op_sel:[1,0]
	v_pk_mul_f32 v[120:121], v[136:137], v[120:121] op_sel:[1,0]
	v_pk_fma_f32 v[118:119], v[154:155], v[118:119], v[158:159]
	v_pk_fma_f32 v[120:121], v[156:157], v[120:121], v[160:161]
	v_cndmask_b32_e32 v119, v250, v119, vcc
	v_cndmask_b32_e32 v118, v250, v118, vcc
	v_cndmask_b32_e32 v121, v250, v121, vcc
	v_cndmask_b32_e32 v120, v250, v120, vcc
	v_cvt_pk_f16_f32 v137, v120, v121
	v_cvt_pk_f16_f32 v136, v118, v119
	v_pk_fma_f32 v[118:119], v[228:229], v[118:119], v[174:175]
	global_store_dwordx2 v[188:189], v[136:137], off
	v_cvt_pk_bf16_f32 v136, v118, v119
	v_lshl_add_u64 v[118:119], v[148:149], 1, s[6:7]
	v_pk_fma_f32 v[120:121], v[226:227], v[120:121], v[176:177]
	s_nop 0
	v_cvt_pk_bf16_f32 v137, v120, v121
	global_store_dwordx2 v[118:119], v[136:137], off
	ds_read_b64 v[120:121], v0 offset:9216
	v_lshlrev_b64 v[136:137], 10, v[204:205]
	v_lshl_add_u64 v[136:137], v[136:137], 0, v[196:197]
	s_waitcnt lgkmcnt(0)
	v_sub_f32_e32 v125, v125, v120
	v_sub_f32_e32 v124, v124, v120
	v_sub_f32_e32 v123, v123, v120
	v_sub_f32_e32 v122, v122, v120
	v_pk_mul_f32 v[122:123], v[120:121], v[122:123] op_sel:[1,0]
	v_pk_mul_f32 v[120:121], v[120:121], v[124:125] op_sel:[1,0]
	v_pk_fma_f32 v[122:123], v[154:155], v[122:123], v[158:159]
	v_pk_fma_f32 v[120:121], v[156:157], v[120:121], v[160:161]
	v_cndmask_b32_e32 v123, v250, v123, vcc
	v_cndmask_b32_e32 v122, v250, v122, vcc
	v_cndmask_b32_e32 v121, v250, v121, vcc
	v_cndmask_b32_e32 v120, v250, v120, vcc
	v_cvt_pk_f16_f32 v125, v120, v121
	v_cvt_pk_f16_f32 v124, v122, v123
	v_pk_fma_f32 v[120:121], v[226:227], v[120:121], v[176:177]
	v_pk_fma_f32 v[122:123], v[228:229], v[122:123], v[174:175]
	global_store_dwordx2 v[186:187], v[124:125], off
	v_cvt_pk_bf16_f32 v122, v122, v123
	v_cvt_pk_bf16_f32 v123, v120, v121
	v_lshl_add_u64 v[120:121], v[136:137], 1, s[6:7]
	global_store_dwordx2 v[120:121], v[122:123], off
	ds_read_b64 v[122:123], v0 offset:9344
	v_lshlrev_b64 v[124:125], 10, v[202:203]
	v_lshl_add_u64 v[124:125], v[124:125], 0, v[196:197]
	s_waitcnt lgkmcnt(0)
	v_sub_f32_e32 v117, v117, v122
	v_sub_f32_e32 v116, v116, v122
	v_sub_f32_e32 v115, v115, v122
	v_sub_f32_e32 v114, v114, v122
	v_pk_mul_f32 v[114:115], v[122:123], v[114:115] op_sel:[1,0]
	v_pk_mul_f32 v[116:117], v[122:123], v[116:117] op_sel:[1,0]
	v_pk_fma_f32 v[114:115], v[154:155], v[114:115], v[158:159]
	v_pk_fma_f32 v[116:117], v[156:157], v[116:117], v[160:161]
	v_cndmask_b32_e32 v115, v250, v115, vcc
	v_cndmask_b32_e32 v114, v250, v114, vcc
	v_cndmask_b32_e32 v117, v250, v117, vcc
	v_cndmask_b32_e32 v116, v250, v116, vcc
	v_cvt_pk_f16_f32 v123, v116, v117
	v_cvt_pk_f16_f32 v122, v114, v115
	v_pk_fma_f32 v[116:117], v[226:227], v[116:117], v[176:177]
	global_store_dwordx2 v[184:185], v[122:123], off
	v_pk_fma_f32 v[114:115], v[228:229], v[114:115], v[174:175]
	s_nop 0
	v_cvt_pk_bf16_f32 v122, v114, v115
	v_cvt_pk_bf16_f32 v123, v116, v117
	ds_read_b64 v[116:117], v0 offset:9472
	v_lshl_add_u64 v[114:115], v[124:125], 1, s[6:7]
	global_store_dwordx2 v[114:115], v[122:123], off
	v_lshlrev_b64 v[122:123], 10, v[200:201]
	v_lshl_add_u64 v[122:123], v[122:123], 0, v[196:197]
	s_waitcnt lgkmcnt(0)
	v_sub_f32_e32 v113, v113, v116
	v_sub_f32_e32 v112, v112, v116
	v_sub_f32_e32 v111, v111, v116
	v_sub_f32_e32 v110, v110, v116
	v_pk_mul_f32 v[110:111], v[116:117], v[110:111] op_sel:[1,0]
	v_pk_mul_f32 v[112:113], v[116:117], v[112:113] op_sel:[1,0]
	v_pk_fma_f32 v[110:111], v[154:155], v[110:111], v[158:159]
	v_pk_fma_f32 v[112:113], v[156:157], v[112:113], v[160:161]
	v_cndmask_b32_e32 v111, v250, v111, vcc
	v_cndmask_b32_e32 v110, v250, v110, vcc
	v_cndmask_b32_e32 v113, v250, v113, vcc
	v_cndmask_b32_e32 v112, v250, v112, vcc
	v_cvt_pk_f16_f32 v117, v112, v113
	v_cvt_pk_f16_f32 v116, v110, v111
	v_pk_fma_f32 v[112:113], v[226:227], v[112:113], v[176:177]
	global_store_dwordx2 v[182:183], v[116:117], off
	v_pk_fma_f32 v[110:111], v[228:229], v[110:111], v[174:175]
	s_nop 0
	v_cvt_pk_bf16_f32 v116, v110, v111
	v_cvt_pk_bf16_f32 v117, v112, v113
	ds_read_b64 v[112:113], v0 offset:9600
	v_lshl_add_u64 v[110:111], v[122:123], 1, s[6:7]
	global_store_dwordx2 v[110:111], v[116:117], off
	v_lshlrev_b64 v[116:117], 10, v[198:199]
	v_lshl_add_u64 v[116:117], v[116:117], 0, v[196:197]
	s_waitcnt lgkmcnt(0)
	v_sub_f32_e32 v109, v109, v112
	v_sub_f32_e32 v108, v108, v112
	v_sub_f32_e32 v107, v107, v112
	v_sub_f32_e32 v106, v106, v112
	v_pk_mul_f32 v[106:107], v[112:113], v[106:107] op_sel:[1,0]
	v_pk_mul_f32 v[108:109], v[112:113], v[108:109] op_sel:[1,0]
	v_pk_fma_f32 v[106:107], v[154:155], v[106:107], v[158:159]
	v_pk_fma_f32 v[108:109], v[156:157], v[108:109], v[160:161]
	v_cndmask_b32_e32 v107, v250, v107, vcc
	v_cndmask_b32_e32 v106, v250, v106, vcc
	v_cndmask_b32_e32 v109, v250, v109, vcc
	v_cndmask_b32_e32 v108, v250, v108, vcc
	v_cvt_pk_f16_f32 v113, v108, v109
	v_cvt_pk_f16_f32 v112, v106, v107
	v_pk_fma_f32 v[106:107], v[228:229], v[106:107], v[174:175]
	global_store_dwordx2 v[180:181], v[112:113], off
	v_cvt_pk_bf16_f32 v112, v106, v107
	v_lshl_add_u64 v[106:107], v[116:117], 1, s[6:7]
	v_pk_fma_f32 v[108:109], v[226:227], v[108:109], v[176:177]
	s_nop 0
	v_cvt_pk_bf16_f32 v113, v108, v109
	global_store_dwordx2 v[106:107], v[112:113], off
	ds_read_b64 v[108:109], v0 offset:8192
	s_waitcnt lgkmcnt(0)
	v_sub_f32_e32 v105, v105, v108
	v_sub_f32_e32 v104, v104, v108
	v_sub_f32_e32 v103, v103, v108
	v_sub_f32_e32 v102, v102, v108
	v_pk_mul_f32 v[102:103], v[108:109], v[102:103] op_sel:[1,0]
	v_pk_mul_f32 v[104:105], v[108:109], v[104:105] op_sel:[1,0]
	v_pk_fma_f32 v[102:103], v[138:139], v[102:103], v[142:143]
	v_pk_fma_f32 v[104:105], v[140:141], v[104:105], v[144:145]
	v_cndmask_b32_e32 v103, v250, v103, vcc
	v_cndmask_b32_e32 v102, v250, v102, vcc
	v_cndmask_b32_e32 v105, v250, v105, vcc
	v_cndmask_b32_e32 v104, v250, v104, vcc
	v_cvt_pk_f16_f32 v109, v104, v105
	v_cvt_pk_f16_f32 v108, v102, v103
	v_pk_fma_f32 v[102:103], v[224:225], v[102:103], v[170:171]
	global_store_dwordx2 v[194:195], v[108:109], off offset:32
	v_pk_fma_f32 v[104:105], v[222:223], v[104:105], v[172:173]
	v_cvt_pk_bf16_f32 v102, v102, v103
	s_nop 0
	v_cvt_pk_bf16_f32 v103, v104, v105
	global_store_dwordx2 v[150:151], v[102:103], off offset:32
	ds_read_b64 v[102:103], v0 offset:8320
	s_waitcnt lgkmcnt(0)
	v_sub_f32_e32 v101, v101, v102
	v_sub_f32_e32 v100, v100, v102
	v_sub_f32_e32 v99, v99, v102
	v_sub_f32_e32 v98, v98, v102
	v_pk_mul_f32 v[98:99], v[102:103], v[98:99] op_sel:[1,0]
	v_pk_mul_f32 v[100:101], v[102:103], v[100:101] op_sel:[1,0]
	v_pk_fma_f32 v[98:99], v[138:139], v[98:99], v[142:143]
	v_pk_fma_f32 v[100:101], v[140:141], v[100:101], v[144:145]
	v_cndmask_b32_e32 v99, v250, v99, vcc
	v_cndmask_b32_e32 v98, v250, v98, vcc
	v_cndmask_b32_e32 v101, v250, v101, vcc
	v_cndmask_b32_e32 v100, v250, v100, vcc
	v_cvt_pk_f16_f32 v103, v100, v101
	v_cvt_pk_f16_f32 v102, v98, v99
	v_pk_fma_f32 v[98:99], v[224:225], v[98:99], v[170:171]
	global_store_dwordx2 v[192:193], v[102:103], off offset:32
	v_pk_fma_f32 v[100:101], v[222:223], v[100:101], v[172:173]
	v_cvt_pk_bf16_f32 v98, v98, v99
	s_nop 0
	v_cvt_pk_bf16_f32 v99, v100, v101
	global_store_dwordx2 v[146:147], v[98:99], off offset:32
	ds_read_b64 v[98:99], v0 offset:8448
	s_waitcnt lgkmcnt(0)
	v_sub_f32_e32 v97, v97, v98
	v_sub_f32_e32 v96, v96, v98
	v_sub_f32_e32 v95, v95, v98
	v_sub_f32_e32 v94, v94, v98
	v_pk_mul_f32 v[94:95], v[98:99], v[94:95] op_sel:[1,0]
	v_pk_mul_f32 v[96:97], v[98:99], v[96:97] op_sel:[1,0]
	v_pk_fma_f32 v[94:95], v[138:139], v[94:95], v[142:143]
	v_pk_fma_f32 v[96:97], v[140:141], v[96:97], v[144:145]
	v_cndmask_b32_e32 v95, v250, v95, vcc
	v_cndmask_b32_e32 v94, v250, v94, vcc
	v_cndmask_b32_e32 v97, v250, v97, vcc
	v_cndmask_b32_e32 v96, v250, v96, vcc
	v_cvt_pk_f16_f32 v99, v96, v97
	v_cvt_pk_f16_f32 v98, v94, v95
	v_pk_fma_f32 v[94:95], v[224:225], v[94:95], v[170:171]
	global_store_dwordx2 v[190:191], v[98:99], off offset:32
	v_pk_fma_f32 v[96:97], v[222:223], v[96:97], v[172:173]
	v_cvt_pk_bf16_f32 v94, v94, v95
	s_nop 0
	v_cvt_pk_bf16_f32 v95, v96, v97
	global_store_dwordx2 v[134:135], v[94:95], off offset:32
	ds_read_b64 v[94:95], v0 offset:8576
	s_waitcnt lgkmcnt(0)
	v_sub_f32_e32 v93, v93, v94
	v_sub_f32_e32 v92, v92, v94
	v_sub_f32_e32 v91, v91, v94
	v_sub_f32_e32 v90, v90, v94
	v_pk_mul_f32 v[90:91], v[94:95], v[90:91] op_sel:[1,0]
	v_pk_mul_f32 v[92:93], v[94:95], v[92:93] op_sel:[1,0]
	v_pk_fma_f32 v[90:91], v[138:139], v[90:91], v[142:143]
	v_pk_fma_f32 v[92:93], v[140:141], v[92:93], v[144:145]
	v_cndmask_b32_e32 v91, v250, v91, vcc
	v_cndmask_b32_e32 v90, v250, v90, vcc
	v_cndmask_b32_e32 v93, v250, v93, vcc
	v_cndmask_b32_e32 v92, v250, v92, vcc
	v_cvt_pk_f16_f32 v95, v92, v93
	v_cvt_pk_f16_f32 v94, v90, v91
	v_pk_fma_f32 v[90:91], v[224:225], v[90:91], v[170:171]
	global_store_dwordx2 v[188:189], v[94:95], off offset:32
	v_pk_fma_f32 v[92:93], v[222:223], v[92:93], v[172:173]
	v_cvt_pk_bf16_f32 v90, v90, v91
	s_nop 0
	v_cvt_pk_bf16_f32 v91, v92, v93
	global_store_dwordx2 v[118:119], v[90:91], off offset:32
	ds_read_b64 v[90:91], v0 offset:9216
	s_waitcnt lgkmcnt(0)
	v_sub_f32_e32 v89, v89, v90
	v_sub_f32_e32 v88, v88, v90
	v_sub_f32_e32 v87, v87, v90
	v_sub_f32_e32 v86, v86, v90
	v_pk_mul_f32 v[86:87], v[90:91], v[86:87] op_sel:[1,0]
	v_pk_mul_f32 v[88:89], v[90:91], v[88:89] op_sel:[1,0]
	v_pk_fma_f32 v[86:87], v[138:139], v[86:87], v[142:143]
	v_pk_fma_f32 v[88:89], v[140:141], v[88:89], v[144:145]
	v_cndmask_b32_e32 v87, v250, v87, vcc
	v_cndmask_b32_e32 v86, v250, v86, vcc
	v_cndmask_b32_e32 v89, v250, v89, vcc
	v_cndmask_b32_e32 v88, v250, v88, vcc
	v_cvt_pk_f16_f32 v91, v88, v89
	v_cvt_pk_f16_f32 v90, v86, v87
	v_pk_fma_f32 v[86:87], v[224:225], v[86:87], v[170:171]
	global_store_dwordx2 v[186:187], v[90:91], off offset:32
	v_pk_fma_f32 v[88:89], v[222:223], v[88:89], v[172:173]
	v_cvt_pk_bf16_f32 v86, v86, v87
	s_nop 0
	v_cvt_pk_bf16_f32 v87, v88, v89
	global_store_dwordx2 v[120:121], v[86:87], off offset:32
	ds_read_b64 v[86:87], v0 offset:9344
	s_waitcnt lgkmcnt(0)
	v_sub_f32_e32 v85, v85, v86
	v_sub_f32_e32 v84, v84, v86
	v_sub_f32_e32 v83, v83, v86
	v_sub_f32_e32 v82, v82, v86
	v_pk_mul_f32 v[82:83], v[86:87], v[82:83] op_sel:[1,0]
	v_pk_mul_f32 v[84:85], v[86:87], v[84:85] op_sel:[1,0]
	v_pk_fma_f32 v[82:83], v[138:139], v[82:83], v[142:143]
	v_pk_fma_f32 v[84:85], v[140:141], v[84:85], v[144:145]
	v_cndmask_b32_e32 v83, v250, v83, vcc
	v_cndmask_b32_e32 v82, v250, v82, vcc
	v_cndmask_b32_e32 v85, v250, v85, vcc
	v_cndmask_b32_e32 v84, v250, v84, vcc
	v_cvt_pk_f16_f32 v87, v84, v85
	v_cvt_pk_f16_f32 v86, v82, v83
	v_pk_fma_f32 v[82:83], v[224:225], v[82:83], v[170:171]
	global_store_dwordx2 v[184:185], v[86:87], off offset:32
	v_pk_fma_f32 v[84:85], v[222:223], v[84:85], v[172:173]
	v_cvt_pk_bf16_f32 v82, v82, v83
	s_nop 0
	v_cvt_pk_bf16_f32 v83, v84, v85
	global_store_dwordx2 v[114:115], v[82:83], off offset:32
	ds_read_b64 v[82:83], v0 offset:9472
	s_waitcnt lgkmcnt(0)
	v_sub_f32_e32 v81, v81, v82
	v_sub_f32_e32 v80, v80, v82
	v_sub_f32_e32 v79, v79, v82
	v_sub_f32_e32 v78, v78, v82
	v_pk_mul_f32 v[78:79], v[82:83], v[78:79] op_sel:[1,0]
	v_pk_mul_f32 v[80:81], v[82:83], v[80:81] op_sel:[1,0]
	v_pk_fma_f32 v[78:79], v[138:139], v[78:79], v[142:143]
	v_pk_fma_f32 v[80:81], v[140:141], v[80:81], v[144:145]
	v_cndmask_b32_e32 v79, v250, v79, vcc
	v_cndmask_b32_e32 v78, v250, v78, vcc
	v_cndmask_b32_e32 v81, v250, v81, vcc
	v_cndmask_b32_e32 v80, v250, v80, vcc
	v_cvt_pk_f16_f32 v83, v80, v81
	v_cvt_pk_f16_f32 v82, v78, v79
	v_pk_fma_f32 v[78:79], v[224:225], v[78:79], v[170:171]
	global_store_dwordx2 v[182:183], v[82:83], off offset:32
	v_pk_fma_f32 v[80:81], v[222:223], v[80:81], v[172:173]
	v_cvt_pk_bf16_f32 v78, v78, v79
	s_nop 0
	v_cvt_pk_bf16_f32 v79, v80, v81
	global_store_dwordx2 v[110:111], v[78:79], off offset:32
	ds_read_b64 v[78:79], v0 offset:9600
	s_waitcnt lgkmcnt(0)
	v_sub_f32_e32 v77, v77, v78
	v_sub_f32_e32 v76, v76, v78
	v_sub_f32_e32 v75, v75, v78
	v_sub_f32_e32 v74, v74, v78
	v_pk_mul_f32 v[74:75], v[78:79], v[74:75] op_sel:[1,0]
	v_pk_mul_f32 v[76:77], v[78:79], v[76:77] op_sel:[1,0]
	v_pk_fma_f32 v[74:75], v[138:139], v[74:75], v[142:143]
	v_pk_fma_f32 v[76:77], v[140:141], v[76:77], v[144:145]
	v_cndmask_b32_e32 v75, v250, v75, vcc
	v_cndmask_b32_e32 v74, v250, v74, vcc
	v_cndmask_b32_e32 v77, v250, v77, vcc
	v_cndmask_b32_e32 v76, v250, v76, vcc
	v_cvt_pk_f16_f32 v79, v76, v77
	v_cvt_pk_f16_f32 v78, v74, v75
	v_pk_fma_f32 v[74:75], v[224:225], v[74:75], v[170:171]
	global_store_dwordx2 v[180:181], v[78:79], off offset:32
	v_pk_fma_f32 v[76:77], v[222:223], v[76:77], v[172:173]
	v_cvt_pk_bf16_f32 v74, v74, v75
	s_nop 0
	v_cvt_pk_bf16_f32 v75, v76, v77
	global_store_dwordx2 v[106:107], v[74:75], off offset:32
	ds_read_b64 v[74:75], v0 offset:8192
	s_waitcnt lgkmcnt(0)
	v_sub_f32_e32 v65, v65, v74
	v_sub_f32_e32 v64, v64, v74
	v_sub_f32_e32 v63, v63, v74
	v_sub_f32_e32 v62, v62, v74
	v_pk_mul_f32 v[62:63], v[74:75], v[62:63] op_sel:[1,0]
	v_pk_mul_f32 v[64:65], v[74:75], v[64:65] op_sel:[1,0]
	v_pk_fma_f32 v[62:63], v[126:127], v[62:63], v[130:131]
	v_pk_fma_f32 v[64:65], v[128:129], v[64:65], v[132:133]
	v_cndmask_b32_e32 v63, v250, v63, vcc
	v_cndmask_b32_e32 v62, v250, v62, vcc
	v_cndmask_b32_e32 v65, v250, v65, vcc
	v_cndmask_b32_e32 v64, v250, v64, vcc
	v_cvt_pk_f16_f32 v75, v64, v65
	v_cvt_pk_f16_f32 v74, v62, v63
	v_pk_fma_f32 v[62:63], v[220:221], v[62:63], v[166:167]
	global_store_dwordx2 v[194:195], v[74:75], off offset:256
	v_pk_fma_f32 v[64:65], v[218:219], v[64:65], v[168:169]
	v_cvt_pk_bf16_f32 v62, v62, v63
	s_nop 0
	v_cvt_pk_bf16_f32 v63, v64, v65
	global_store_dwordx2 v[150:151], v[62:63], off offset:256
	ds_read_b64 v[62:63], v0 offset:8320
	s_waitcnt lgkmcnt(0)
	v_sub_f32_e32 v65, v73, v62
	v_sub_f32_e32 v64, v72, v62
	v_sub_f32_e32 v71, v71, v62
	v_sub_f32_e32 v70, v70, v62
	v_pk_mul_f32 v[70:71], v[62:63], v[70:71] op_sel:[1,0]
	v_pk_mul_f32 v[62:63], v[62:63], v[64:65] op_sel:[1,0]
	v_pk_fma_f32 v[64:65], v[126:127], v[70:71], v[130:131]
	v_pk_fma_f32 v[62:63], v[128:129], v[62:63], v[132:133]
	v_cndmask_b32_e32 v65, v250, v65, vcc
	v_cndmask_b32_e32 v64, v250, v64, vcc
	v_cndmask_b32_e32 v63, v250, v63, vcc
	v_cndmask_b32_e32 v62, v250, v62, vcc
	v_cvt_pk_f16_f32 v71, v62, v63
	v_cvt_pk_f16_f32 v70, v64, v65
	v_pk_fma_f32 v[62:63], v[218:219], v[62:63], v[168:169]
	v_pk_fma_f32 v[64:65], v[220:221], v[64:65], v[166:167]
	global_store_dwordx2 v[192:193], v[70:71], off offset:256
	v_cvt_pk_bf16_f32 v64, v64, v65
	v_cvt_pk_bf16_f32 v65, v62, v63
	ds_read_b64 v[62:63], v0 offset:8448
	global_store_dwordx2 v[146:147], v[64:65], off offset:256
	s_waitcnt lgkmcnt(0)
	v_sub_f32_e32 v65, v69, v62
	v_sub_f32_e32 v64, v68, v62
	v_sub_f32_e32 v67, v67, v62
	v_sub_f32_e32 v66, v66, v62
	v_pk_mul_f32 v[66:67], v[62:63], v[66:67] op_sel:[1,0]
	v_pk_mul_f32 v[62:63], v[62:63], v[64:65] op_sel:[1,0]
	v_pk_fma_f32 v[64:65], v[126:127], v[66:67], v[130:131]
	v_pk_fma_f32 v[62:63], v[128:129], v[62:63], v[132:133]
	v_cndmask_b32_e32 v65, v250, v65, vcc
	v_cndmask_b32_e32 v64, v250, v64, vcc
	v_cndmask_b32_e32 v63, v250, v63, vcc
	v_cndmask_b32_e32 v62, v250, v62, vcc
	v_cvt_pk_f16_f32 v67, v62, v63
	v_cvt_pk_f16_f32 v66, v64, v65
	v_pk_fma_f32 v[62:63], v[218:219], v[62:63], v[168:169]
	v_pk_fma_f32 v[64:65], v[220:221], v[64:65], v[166:167]
	global_store_dwordx2 v[190:191], v[66:67], off offset:256
	v_cvt_pk_bf16_f32 v64, v64, v65
	v_cvt_pk_bf16_f32 v65, v62, v63
	ds_read_b64 v[62:63], v0 offset:8576
	global_store_dwordx2 v[134:135], v[64:65], off offset:256
	s_waitcnt lgkmcnt(0)
	v_sub_f32_e32 v61, v61, v62
	v_sub_f32_e32 v60, v60, v62
	v_sub_f32_e32 v59, v59, v62
	v_sub_f32_e32 v58, v58, v62
	v_pk_mul_f32 v[58:59], v[62:63], v[58:59] op_sel:[1,0]
	v_pk_mul_f32 v[60:61], v[62:63], v[60:61] op_sel:[1,0]
	v_pk_fma_f32 v[58:59], v[126:127], v[58:59], v[130:131]
	v_pk_fma_f32 v[60:61], v[128:129], v[60:61], v[132:133]
	v_cndmask_b32_e32 v59, v250, v59, vcc
	v_cndmask_b32_e32 v58, v250, v58, vcc
	v_cndmask_b32_e32 v61, v250, v61, vcc
	v_cndmask_b32_e32 v60, v250, v60, vcc
	v_cvt_pk_f16_f32 v63, v60, v61
	v_cvt_pk_f16_f32 v62, v58, v59
	v_pk_fma_f32 v[58:59], v[220:221], v[58:59], v[166:167]
	global_store_dwordx2 v[188:189], v[62:63], off offset:256
	v_pk_fma_f32 v[60:61], v[218:219], v[60:61], v[168:169]
	v_cvt_pk_bf16_f32 v58, v58, v59
	s_nop 0
	v_cvt_pk_bf16_f32 v59, v60, v61
	global_store_dwordx2 v[118:119], v[58:59], off offset:256
	ds_read_b64 v[58:59], v0 offset:9216
	s_waitcnt lgkmcnt(0)
	v_sub_f32_e32 v57, v57, v58
	v_sub_f32_e32 v56, v56, v58
	v_sub_f32_e32 v55, v55, v58
	v_sub_f32_e32 v54, v54, v58
	v_pk_mul_f32 v[54:55], v[58:59], v[54:55] op_sel:[1,0]
	v_pk_mul_f32 v[56:57], v[58:59], v[56:57] op_sel:[1,0]
	v_pk_fma_f32 v[54:55], v[126:127], v[54:55], v[130:131]
	v_pk_fma_f32 v[56:57], v[128:129], v[56:57], v[132:133]
	v_cndmask_b32_e32 v55, v250, v55, vcc
	v_cndmask_b32_e32 v54, v250, v54, vcc
	v_cndmask_b32_e32 v57, v250, v57, vcc
	v_cndmask_b32_e32 v56, v250, v56, vcc
	v_cvt_pk_f16_f32 v59, v56, v57
	v_cvt_pk_f16_f32 v58, v54, v55
	v_pk_fma_f32 v[54:55], v[220:221], v[54:55], v[166:167]
	global_store_dwordx2 v[186:187], v[58:59], off offset:256
	v_pk_fma_f32 v[56:57], v[218:219], v[56:57], v[168:169]
	v_cvt_pk_bf16_f32 v54, v54, v55
	s_nop 0
	v_cvt_pk_bf16_f32 v55, v56, v57
	global_store_dwordx2 v[120:121], v[54:55], off offset:256
	ds_read_b64 v[54:55], v0 offset:9344
	s_waitcnt lgkmcnt(0)
	v_sub_f32_e32 v53, v53, v54
	v_sub_f32_e32 v52, v52, v54
	v_sub_f32_e32 v51, v51, v54
	v_sub_f32_e32 v50, v50, v54
	v_pk_mul_f32 v[50:51], v[54:55], v[50:51] op_sel:[1,0]
	v_pk_mul_f32 v[52:53], v[54:55], v[52:53] op_sel:[1,0]
	v_pk_fma_f32 v[50:51], v[126:127], v[50:51], v[130:131]
	v_pk_fma_f32 v[52:53], v[128:129], v[52:53], v[132:133]
	v_cndmask_b32_e32 v51, v250, v51, vcc
	v_cndmask_b32_e32 v50, v250, v50, vcc
	v_cndmask_b32_e32 v53, v250, v53, vcc
	v_cndmask_b32_e32 v52, v250, v52, vcc
	v_cvt_pk_f16_f32 v55, v52, v53
	v_cvt_pk_f16_f32 v54, v50, v51
	v_pk_fma_f32 v[50:51], v[220:221], v[50:51], v[166:167]
	global_store_dwordx2 v[184:185], v[54:55], off offset:256
	v_pk_fma_f32 v[52:53], v[218:219], v[52:53], v[168:169]
	v_cvt_pk_bf16_f32 v50, v50, v51
	s_nop 0
	v_cvt_pk_bf16_f32 v51, v52, v53
	global_store_dwordx2 v[114:115], v[50:51], off offset:256
	ds_read_b64 v[50:51], v0 offset:9472
	s_waitcnt lgkmcnt(0)
	v_sub_f32_e32 v49, v49, v50
	v_sub_f32_e32 v48, v48, v50
	v_sub_f32_e32 v47, v47, v50
	v_sub_f32_e32 v46, v46, v50
	v_pk_mul_f32 v[46:47], v[50:51], v[46:47] op_sel:[1,0]
	v_pk_mul_f32 v[48:49], v[50:51], v[48:49] op_sel:[1,0]
	v_pk_fma_f32 v[46:47], v[126:127], v[46:47], v[130:131]
	v_pk_fma_f32 v[48:49], v[128:129], v[48:49], v[132:133]
	v_cndmask_b32_e32 v47, v250, v47, vcc
	v_cndmask_b32_e32 v46, v250, v46, vcc
	v_cndmask_b32_e32 v49, v250, v49, vcc
	v_cndmask_b32_e32 v48, v250, v48, vcc
	v_cvt_pk_f16_f32 v51, v48, v49
	v_cvt_pk_f16_f32 v50, v46, v47
	v_pk_fma_f32 v[46:47], v[220:221], v[46:47], v[166:167]
	global_store_dwordx2 v[182:183], v[50:51], off offset:256
	v_pk_fma_f32 v[48:49], v[218:219], v[48:49], v[168:169]
	v_cvt_pk_bf16_f32 v46, v46, v47
	s_nop 0
	v_cvt_pk_bf16_f32 v47, v48, v49
	global_store_dwordx2 v[110:111], v[46:47], off offset:256
	ds_read_b64 v[46:47], v0 offset:9600
	s_waitcnt lgkmcnt(0)
	v_sub_f32_e32 v41, v41, v46
	v_sub_f32_e32 v40, v40, v46
	v_sub_f32_e32 v39, v39, v46
	v_sub_f32_e32 v38, v38, v46
	v_pk_mul_f32 v[38:39], v[46:47], v[38:39] op_sel:[1,0]
	v_pk_mul_f32 v[40:41], v[46:47], v[40:41] op_sel:[1,0]
	v_pk_fma_f32 v[38:39], v[126:127], v[38:39], v[130:131]
	v_pk_fma_f32 v[40:41], v[128:129], v[40:41], v[132:133]
	v_cndmask_b32_e32 v39, v250, v39, vcc
	v_cndmask_b32_e32 v38, v250, v38, vcc
	v_cndmask_b32_e32 v41, v250, v41, vcc
	v_cndmask_b32_e32 v40, v250, v40, vcc
	v_cvt_pk_f16_f32 v47, v40, v41
	v_cvt_pk_f16_f32 v46, v38, v39
	v_pk_fma_f32 v[38:39], v[220:221], v[38:39], v[166:167]
	global_store_dwordx2 v[180:181], v[46:47], off offset:256
	v_pk_fma_f32 v[40:41], v[218:219], v[40:41], v[168:169]
	v_cvt_pk_bf16_f32 v38, v38, v39
	s_nop 0
	v_cvt_pk_bf16_f32 v39, v40, v41
	global_store_dwordx2 v[106:107], v[38:39], off offset:256
	ds_read_b64 v[38:39], v0 offset:8192
	s_waitcnt lgkmcnt(0)
	v_sub_f32_e32 v21, v21, v38
	v_sub_f32_e32 v20, v20, v38
	v_sub_f32_e32 v19, v19, v38
	v_sub_f32_e32 v18, v18, v38
	v_pk_mul_f32 v[18:19], v[38:39], v[18:19] op_sel:[1,0]
	v_pk_mul_f32 v[20:21], v[38:39], v[20:21] op_sel:[1,0]
	v_pk_fma_f32 v[18:19], v[14:15], v[18:19], v[22:23]
	v_pk_fma_f32 v[20:21], v[16:17], v[20:21], v[24:25]
	v_cndmask_b32_e32 v19, v250, v19, vcc
	v_cndmask_b32_e32 v18, v250, v18, vcc
	v_cndmask_b32_e32 v21, v250, v21, vcc
	v_cndmask_b32_e32 v20, v250, v20, vcc
	v_cvt_pk_f16_f32 v39, v20, v21
	v_cvt_pk_f16_f32 v38, v18, v19
	v_pk_fma_f32 v[18:19], v[216:217], v[18:19], v[162:163]
	global_store_dwordx2 v[194:195], v[38:39], off offset:288
	v_pk_fma_f32 v[20:21], v[214:215], v[20:21], v[164:165]
	v_cvt_pk_bf16_f32 v18, v18, v19
	s_nop 0
	v_cvt_pk_bf16_f32 v19, v20, v21
	global_store_dwordx2 v[150:151], v[18:19], off offset:288
	ds_read_b64 v[18:19], v0 offset:8320
	s_waitcnt lgkmcnt(0)
	v_sub_f32_e32 v13, v13, v18
	v_sub_f32_e32 v12, v12, v18
	v_sub_f32_e32 v11, v11, v18
	v_sub_f32_e32 v10, v10, v18
	v_pk_mul_f32 v[10:11], v[18:19], v[10:11] op_sel:[1,0]
	v_pk_mul_f32 v[12:13], v[18:19], v[12:13] op_sel:[1,0]
	v_pk_fma_f32 v[10:11], v[14:15], v[10:11], v[22:23]
	v_pk_fma_f32 v[12:13], v[16:17], v[12:13], v[24:25]
	v_cndmask_b32_e32 v11, v250, v11, vcc
	v_cndmask_b32_e32 v10, v250, v10, vcc
	v_cndmask_b32_e32 v13, v250, v13, vcc
	v_cndmask_b32_e32 v12, v250, v12, vcc
	v_cvt_pk_f16_f32 v19, v12, v13
	v_cvt_pk_f16_f32 v18, v10, v11
	v_pk_fma_f32 v[10:11], v[216:217], v[10:11], v[162:163]
	global_store_dwordx2 v[192:193], v[18:19], off offset:288
	v_pk_fma_f32 v[12:13], v[214:215], v[12:13], v[164:165]
	v_cvt_pk_bf16_f32 v10, v10, v11
	s_nop 0
	v_cvt_pk_bf16_f32 v11, v12, v13
	global_store_dwordx2 v[146:147], v[10:11], off offset:288
	ds_read_b64 v[10:11], v0 offset:8448
	s_waitcnt lgkmcnt(0)
	v_sub_f32_e32 v13, v45, v10
	v_sub_f32_e32 v12, v44, v10
	v_sub_f32_e32 v19, v43, v10
	v_sub_f32_e32 v18, v42, v10
	v_pk_mul_f32 v[18:19], v[10:11], v[18:19] op_sel:[1,0]
	v_pk_mul_f32 v[10:11], v[10:11], v[12:13] op_sel:[1,0]
	v_pk_fma_f32 v[12:13], v[14:15], v[18:19], v[22:23]
	v_pk_fma_f32 v[10:11], v[16:17], v[10:11], v[24:25]
	v_cndmask_b32_e32 v13, v250, v13, vcc
	v_cndmask_b32_e32 v12, v250, v12, vcc
	v_cndmask_b32_e32 v11, v250, v11, vcc
	v_cndmask_b32_e32 v10, v250, v10, vcc
	v_cvt_pk_f16_f32 v19, v10, v11
	v_cvt_pk_f16_f32 v18, v12, v13
	v_pk_fma_f32 v[10:11], v[214:215], v[10:11], v[164:165]
	v_pk_fma_f32 v[12:13], v[216:217], v[12:13], v[162:163]
	global_store_dwordx2 v[190:191], v[18:19], off offset:288
	v_cvt_pk_bf16_f32 v12, v12, v13
	v_cvt_pk_bf16_f32 v13, v10, v11
	ds_read_b64 v[10:11], v0 offset:8576
	global_store_dwordx2 v[134:135], v[12:13], off offset:288
	s_waitcnt lgkmcnt(0)
	v_sub_f32_e32 v13, v37, v10
	v_sub_f32_e32 v12, v36, v10
	v_sub_f32_e32 v19, v35, v10
	v_sub_f32_e32 v18, v34, v10
	v_pk_mul_f32 v[18:19], v[10:11], v[18:19] op_sel:[1,0]
	v_pk_mul_f32 v[10:11], v[10:11], v[12:13] op_sel:[1,0]
	v_pk_fma_f32 v[12:13], v[14:15], v[18:19], v[22:23]
	v_pk_fma_f32 v[10:11], v[16:17], v[10:11], v[24:25]
	v_cndmask_b32_e32 v13, v250, v13, vcc
	v_cndmask_b32_e32 v12, v250, v12, vcc
	v_cndmask_b32_e32 v11, v250, v11, vcc
	v_cndmask_b32_e32 v10, v250, v10, vcc
	v_cvt_pk_f16_f32 v19, v10, v11
	v_cvt_pk_f16_f32 v18, v12, v13
	v_pk_fma_f32 v[12:13], v[216:217], v[12:13], v[162:163]
	global_store_dwordx2 v[188:189], v[18:19], off offset:288
	v_pk_fma_f32 v[10:11], v[214:215], v[10:11], v[164:165]
	v_cvt_pk_bf16_f32 v12, v12, v13
	s_nop 0
	v_cvt_pk_bf16_f32 v13, v10, v11
	global_store_dwordx2 v[118:119], v[12:13], off offset:288
	ds_read_b64 v[10:11], v0 offset:9216
	s_waitcnt lgkmcnt(0)
	v_sub_f32_e32 v13, v33, v10
	v_sub_f32_e32 v12, v32, v10
	v_sub_f32_e32 v19, v31, v10
	v_sub_f32_e32 v18, v30, v10
	v_pk_mul_f32 v[18:19], v[10:11], v[18:19] op_sel:[1,0]
	v_pk_mul_f32 v[10:11], v[10:11], v[12:13] op_sel:[1,0]
	v_pk_fma_f32 v[12:13], v[14:15], v[18:19], v[22:23]
	v_pk_fma_f32 v[10:11], v[16:17], v[10:11], v[24:25]
	v_cndmask_b32_e32 v13, v250, v13, vcc
	v_cndmask_b32_e32 v12, v250, v12, vcc
	v_cndmask_b32_e32 v11, v250, v11, vcc
	v_cndmask_b32_e32 v10, v250, v10, vcc
	v_cvt_pk_f16_f32 v19, v10, v11
	v_cvt_pk_f16_f32 v18, v12, v13
	v_pk_fma_f32 v[10:11], v[214:215], v[10:11], v[164:165]
	v_pk_fma_f32 v[12:13], v[216:217], v[12:13], v[162:163]
	global_store_dwordx2 v[186:187], v[18:19], off offset:288
	v_cvt_pk_bf16_f32 v12, v12, v13
	v_cvt_pk_bf16_f32 v13, v10, v11
	ds_read_b64 v[10:11], v0 offset:9344
	global_store_dwordx2 v[120:121], v[12:13], off offset:288
	s_waitcnt lgkmcnt(0)
	v_sub_f32_e32 v13, v29, v10
	v_sub_f32_e32 v12, v28, v10
	v_sub_f32_e32 v19, v27, v10
	v_sub_f32_e32 v18, v26, v10
	v_pk_mul_f32 v[18:19], v[10:11], v[18:19] op_sel:[1,0]
	v_pk_mul_f32 v[10:11], v[10:11], v[12:13] op_sel:[1,0]
	v_pk_fma_f32 v[12:13], v[14:15], v[18:19], v[22:23]
	v_pk_fma_f32 v[10:11], v[16:17], v[10:11], v[24:25]
	v_cndmask_b32_e32 v13, v250, v13, vcc
	v_cndmask_b32_e32 v12, v250, v12, vcc
	v_cndmask_b32_e32 v11, v250, v11, vcc
	v_cndmask_b32_e32 v10, v250, v10, vcc
	v_cvt_pk_f16_f32 v19, v10, v11
	v_cvt_pk_f16_f32 v18, v12, v13
	v_pk_fma_f32 v[10:11], v[214:215], v[10:11], v[164:165]
	v_pk_fma_f32 v[12:13], v[216:217], v[12:13], v[162:163]
	global_store_dwordx2 v[184:185], v[18:19], off offset:288
	v_cvt_pk_bf16_f32 v12, v12, v13
	v_cvt_pk_bf16_f32 v13, v10, v11
	ds_read_b64 v[10:11], v0 offset:9472
	global_store_dwordx2 v[114:115], v[12:13], off offset:288
	s_waitcnt lgkmcnt(0)
	v_sub_f32_e32 v9, v9, v10
	v_sub_f32_e32 v8, v8, v10
	v_sub_f32_e32 v7, v7, v10
	v_sub_f32_e32 v6, v6, v10
	v_pk_mul_f32 v[6:7], v[10:11], v[6:7] op_sel:[1,0]
	v_pk_mul_f32 v[8:9], v[10:11], v[8:9] op_sel:[1,0]
	v_pk_fma_f32 v[6:7], v[14:15], v[6:7], v[22:23]
	v_pk_fma_f32 v[8:9], v[16:17], v[8:9], v[24:25]
	v_cndmask_b32_e32 v7, v250, v7, vcc
	v_cndmask_b32_e32 v6, v250, v6, vcc
	v_cndmask_b32_e32 v9, v250, v9, vcc
	v_cndmask_b32_e32 v8, v250, v8, vcc
	v_cvt_pk_f16_f32 v11, v8, v9
	v_cvt_pk_f16_f32 v10, v6, v7
	v_pk_fma_f32 v[6:7], v[216:217], v[6:7], v[162:163]
	global_store_dwordx2 v[182:183], v[10:11], off offset:288
	v_pk_fma_f32 v[8:9], v[214:215], v[8:9], v[164:165]
	v_cvt_pk_bf16_f32 v6, v6, v7
	s_nop 0
	v_cvt_pk_bf16_f32 v7, v8, v9
	global_store_dwordx2 v[110:111], v[6:7], off offset:288
	ds_read_b64 v[6:7], v0 offset:9600
	s_waitcnt lgkmcnt(0)
	v_sub_f32_e32 v5, v5, v6
	v_sub_f32_e32 v4, v4, v6
	v_sub_f32_e32 v3, v3, v6
	v_sub_f32_e32 v2, v2, v6
	v_pk_mul_f32 v[2:3], v[6:7], v[2:3] op_sel:[1,0]
	v_pk_mul_f32 v[4:5], v[6:7], v[4:5] op_sel:[1,0]
	v_pk_fma_f32 v[2:3], v[14:15], v[2:3], v[22:23]
	v_pk_fma_f32 v[4:5], v[16:17], v[4:5], v[24:25]
	v_cndmask_b32_e32 v3, v250, v3, vcc
	v_cndmask_b32_e32 v2, v250, v2, vcc
	v_cndmask_b32_e32 v5, v250, v5, vcc
	v_cndmask_b32_e32 v4, v250, v4, vcc
	v_cvt_pk_f16_f32 v7, v4, v5
	v_cvt_pk_f16_f32 v6, v2, v3
	v_pk_fma_f32 v[2:3], v[216:217], v[2:3], v[162:163]
	global_store_dwordx2 v[180:181], v[6:7], off offset:288
	v_pk_fma_f32 v[4:5], v[214:215], v[4:5], v[164:165]
	v_cvt_pk_bf16_f32 v2, v2, v3
	s_nop 0
	v_cvt_pk_bf16_f32 v3, v4, v5
	global_store_dwordx2 v[106:107], v[2:3], off offset:288
